# attention key loop: activity test and stage predicate hoisted above the B1 barrier (loop-edge edit)
# speedup vs baseline: 1.0026x; 1.0014x over previous
; __device__ __forceinline__ void phase_attn(KP P, char* smem, const int wv) {
;     ...
; #pragma unroll 1
;     for (int kt = 0; kt < nkt; ++kt) {
;       const bool act = wave_valid && kt < my_nkt;
;       lds_barrier();
;       if (kt + 2 < nkt) ATT_STAGE((kt + 2) & 3, kt + 2);
;       if (act) ATT_S_SOFTMAX(kt & 3);
.LBB0_61:
	s_add_i32 s24, s26, 2
	s_cmp_ge_i32 s24, s67
	s_cselect_b64 s[22:23], -1, 0
	v_cmp_lt_i32_e32 vcc, s26, v137
	s_and_b64 s[26:27], s[6:7], vcc
	v_cndmask_b32_e64 v98, 0, 1, s[26:27]
	v_cmp_ne_u32_e64 s[8:9], 1, v98
	s_waitcnt lgkmcnt(0)
	s_barrier
	s_and_b64 vcc, exec, s[22:23]
	s_cbranch_vccnz .LBB0_63
	s_add_i32 s25, s19, 0x10000
	s_and_b32 s25, s25, 0x18000
	s_add_i32 s25, s43, s25
	s_mov_b32 m0, s25
	s_nop 0
	global_load_lds_dwordx4 v[150:151], off
	s_add_i32 m0, s25, 0x400
	s_nop 0
	global_load_lds_dwordx4 v[144:145], off
	s_add_i32 m0, s25, 0x4000
	s_nop 0
	global_load_lds_dwordx4 v[142:143], off
	s_add_i32 m0, s25, 0x4400
	s_nop 0
	global_load_lds_dwordx4 v[140:141], off
.LBB0_63:
	s_andn2_b64 vcc, exec, s[26:27]
	s_cbranch_vccnz .LBB0_69
	s_and_b32 s25, s19, 0x18000
	s_add_i32 s25, s64, s25
	s_setprio 1
	v_add_u32_e32 v106, s25, v139
	ds_read_b128 v[2:5], v106
	ds_read_b128 v[10:13], v106 offset:512
	v_add_u32_e32 v110, s25, v153
	ds_read_b128 v[14:17], v110
	ds_read_b128 v[98:101], v110 offset:512
	s_waitcnt lgkmcnt(0)
	v_mfma_f32_16x16x32_bf16 v[6:9], v[2:5], v[82:85], 0
	v_mfma_f32_16x16x32_bf16 v[2:5], v[2:5], v[90:93], 0
	v_mfma_f32_16x16x32_bf16 v[102:105], v[14:17], v[94:97], v[2:5]
	v_mfma_f32_16x16x32_bf16 v[2:5], v[10:13], v[82:85], 0
	v_mfma_f32_16x16x32_bf16 v[10:13], v[10:13], v[90:93], 0
	v_mfma_f32_16x16x32_bf16 v[2:5], v[98:101], v[86:89], v[2:5]
	v_mfma_f32_16x16x32_bf16 v[98:101], v[98:101], v[94:97], v[10:13]
	s_nop 5
	ds_read_b128 v[10:13], v106 offset:4096
	ds_read_b128 v[156:159], v106 offset:4608
	ds_read_b128 v[106:109], v110 offset:4096
	ds_read_b128 v[160:163], v110 offset:4608
	v_mfma_f32_16x16x32_bf16 v[6:9], v[14:17], v[86:89], v[6:9]
	s_waitcnt lgkmcnt(0)
	v_mfma_f32_16x16x32_bf16 v[14:17], v[10:13], v[82:85], 0
	v_mfma_f32_16x16x32_bf16 v[10:13], v[10:13], v[90:93], 0
	v_mfma_f32_16x16x32_bf16 v[110:113], v[106:109], v[86:89], v[14:17]
	v_mfma_f32_16x16x32_bf16 v[14:17], v[106:109], v[94:97], v[10:13]
	v_mfma_f32_16x16x32_bf16 v[10:13], v[156:159], v[82:85], 0
	v_mfma_f32_16x16x32_bf16 v[106:109], v[160:163], v[86:89], v[10:13]
	v_mfma_f32_16x16x32_bf16 v[10:13], v[156:159], v[90:93], 0
	v_mfma_f32_16x16x32_bf16 v[10:13], v[160:163], v[94:97], v[10:13]
	v_max_f32_e32 v156, v7, v7
	v_max_f32_e32 v157, v6, v6
	v_max_f32_e32 v156, v157, v156
	v_max3_f32 v156, v156, v8, v9
	v_max3_f32 v156, v156, v2, v3
	v_max3_f32 v156, v156, v4, v5
	v_max3_f32 v156, v156, v110, v111
	v_max3_f32 v156, v156, v112, v113
	v_max3_f32 v156, v156, v106, v107
	v_max3_f32 v156, v156, v108, v109
	v_sub_f32_e32 v157, v156, v154
	v_cmp_lt_f32_e32 vcc, s60, v157
	s_cbranch_vccz .LBB0_66
	v_mov_b32_e32 v157, v156
	s_nop 1
	v_permlane16_swap_b32_e32 v156, v157
	v_max_f32_e32 v157, v157, v157
	v_max_f32_e32 v156, v156, v156
	v_max_f32_e32 v156, v156, v157
	v_mov_b32_e32 v157, v156
	s_nop 1
	v_permlane32_swap_b32_e32 v156, v157
	v_max3_f32 v156, v154, v156, v157
	v_sub_f32_e32 v154, v154, v156
	v_exp_f32_e32 v154, v154
	s_nop 0
	v_mul_f32_e32 v115, v115, v154
	v_pk_mul_f32 v[80:81], v[80:81], v[154:155] op_sel_hi:[1,0]
	v_pk_mul_f32 v[78:79], v[78:79], v[154:155] op_sel_hi:[1,0]
	v_pk_mul_f32 v[76:77], v[76:77], v[154:155] op_sel_hi:[1,0]
	v_pk_mul_f32 v[74:75], v[74:75], v[154:155] op_sel_hi:[1,0]
	v_pk_mul_f32 v[72:73], v[72:73], v[154:155] op_sel_hi:[1,0]
	v_pk_mul_f32 v[70:71], v[70:71], v[154:155] op_sel_hi:[1,0]
	v_pk_mul_f32 v[68:69], v[68:69], v[154:155] op_sel_hi:[1,0]
	v_pk_mul_f32 v[66:67], v[66:67], v[154:155] op_sel_hi:[1,0]
	v_pk_mul_f32 v[64:65], v[64:65], v[154:155] op_sel_hi:[1,0]
	v_pk_mul_f32 v[62:63], v[62:63], v[154:155] op_sel_hi:[1,0]
	v_pk_mul_f32 v[60:61], v[60:61], v[154:155] op_sel_hi:[1,0]
	v_pk_mul_f32 v[58:59], v[58:59], v[154:155] op_sel_hi:[1,0]
	v_pk_mul_f32 v[56:57], v[56:57], v[154:155] op_sel_hi:[1,0]
	v_pk_mul_f32 v[54:55], v[54:55], v[154:155] op_sel_hi:[1,0]
	v_pk_mul_f32 v[52:53], v[52:53], v[154:155] op_sel_hi:[1,0]
	v_pk_mul_f32 v[50:51], v[50:51], v[154:155] op_sel_hi:[1,0]
	v_mov_b32_e32 v154, v156
